# P1: MOD reduction loads issued up front, consumed (adds+stores) after the first norm staging so its two round trips overlap the staging loads
# speedup vs baseline: 1.0051x; 1.0051x over previous
.LBB0_82:
	s_or_b64 exec, exec, s[0:1]
	v_mov_b32_e32 v2, v250
	s_mov_b64 s[0:1], 0x36000
	v_ashrrev_i32_e32 v3, 31, v2
	v_lshl_add_u64 v[0:1], s[88:89], 0, v[2:3]
	v_cmp_gt_u64_e32 vcc, s[0:1], v[0:1]
	s_and_saveexec_b64 s[4:5], vcc
	v_readlane_b32 s12, v254, 2
	v_readlane_b32 s18, v254, 8
	v_readlane_b32 s19, v254, 9
	v_readlane_b32 s13, v254, 3
	v_readlane_b32 s14, v254, 4
	v_readlane_b32 s15, v254, 5
	v_readlane_b32 s16, v254, 6
	v_readlane_b32 s17, v254, 7
	v_readlane_b32 s20, v254, 10
	v_readlane_b32 s21, v254, 11
	v_readlane_b32 s22, v254, 12
	v_readlane_b32 s23, v254, 13
	v_readlane_b32 s24, v254, 14
	v_readlane_b32 s25, v254, 15
	v_readlane_b32 s26, v254, 16
	v_readlane_b32 s27, v254, 17
	s_cbranch_execz .LBB0_85
	s_lshl_b64 s[0:1], s[96:97], 11
	s_add_u32 s0, s50, s0
	s_addc_u32 s1, s51, s1
	v_lshl_add_u64 v[2:3], v[2:3], 2, s[0:1]
	s_mov_b64 s[0:1], 0x4780000
	v_lshl_add_u64 v[2:3], v[2:3], 0, s[0:1]
	s_lshl_b64 s[6:7], s[92:93], 11
	s_mov_b64 s[8:9], 0
	s_mov_b64 s[12:13], 0x1b000
	s_mov_b32 s2, 0xaaaaaaab
	v_mov_b32_e32 v6, 0x1800
	v_mov_b32_e32 v5, 0
	s_movk_i32 s3, 0x6000
	v_mov_b32_e32 v7, 0x48
	v_mov_b32_e32 v8, 0x5a
	v_mov_b32_e32 v9, 0x6c
	v_mov_b32_e32 v10, 0x7e
	v_mov_b32_e32 v11, 0x90
	v_mov_b32_e32 v12, 0xa2
	v_mov_b32_e32 v13, 0xb4
	v_mov_b32_e32 v14, 0xc6
	v_mov_b32_e32 v15, 0xd8
	v_mov_b32_e32 v16, 0xea
	v_bfrev_b32_e32 v17, 0.5
	v_mov_b32_e32 v18, 0x10e
	s_mov_b64 s[16:17], 0x35fff
	s_mov_b32 s100, 0
	s_cmpk_eq_u32 s92, 0x100
	s_cbranch_scc0 .LBB0_84
	s_mov_b32 s100, 1
	v_add_u32_e32 v4, 0xfffe5000, v0
	v_cmp_gt_u64_e32 vcc, s[12:13], v[0:1]
	s_mov_b64 s[0:1], 0x1afff
	v_cmp_lt_u64_e64 s[0:1], s[0:1], v[0:1]
	v_cndmask_b32_e32 v4, v4, v0, vcc
	v_mul_hi_u32 v29, v4, s2
	v_lshrrev_b32_e32 v29, 12, v29
	v_cndmask_b32_e64 v20, 0, 18, s[0:1]
	v_mul_u32_u24_e32 v30, 0x1800, v29
	v_mov_b32_e32 v21, v5
	v_cndmask_b32_e64 v19, 0, v6, s[0:1]
	v_cndmask_b32_e64 v22, 36, 54, s[0:1]
	v_cndmask_b32_e64 v23, v7, v8, s[0:1]
	v_cndmask_b32_e64 v24, v9, v10, s[0:1]
	v_cndmask_b32_e64 v25, v11, v12, s[0:1]
	v_cndmask_b32_e64 v26, v13, v14, s[0:1]
	v_cndmask_b32_e64 v27, v15, v16, s[0:1]
	v_cndmask_b32_e64 v28, v17, v18, s[0:1]
	v_add_u32_e32 v31, v20, v29
	v_sub_u32_e32 v20, v4, v30
	v_add_u32_e32 v32, v22, v29
	v_add_u32_e32 v33, v23, v29
	v_add_u32_e32 v34, v24, v29
	v_add_u32_e32 v35, v25, v29
	v_add_u32_e32 v36, v26, v29
	v_add_u32_e32 v37, v27, v29
	v_add_u32_e32 v38, v28, v29
	v_add_u32_e32 v4, v20, v19
	v_lshl_add_u64 v[20:21], v[20:21], 2, s[10:11]
	v_lshl_add_u64 v[22:23], v[4:5], 2, s[18:19]
	v_mad_u64_u32 v[24:25], s[0:1], v31, s3, v[20:21]
	v_mad_u64_u32 v[26:27], s[0:1], v32, s3, v[20:21]
	v_mad_u64_u32 v[28:29], s[0:1], v33, s3, v[20:21]
	v_mad_u64_u32 v[30:31], s[0:1], v34, s3, v[20:21]
	v_mad_u64_u32 v[32:33], s[0:1], v35, s3, v[20:21]
	v_mad_u64_u32 v[34:35], s[0:1], v36, s3, v[20:21]
	v_mad_u64_u32 v[36:37], s[0:1], v37, s3, v[20:21]
	v_mad_u64_u32 v[20:21], s[0:1], v38, s3, v[20:21]
	global_load_dword v144, v[22:23], off
	global_load_dword v145, v[24:25], off
	s_nop 0
	global_load_dword v146, v[26:27], off
	global_load_dword v147, v[28:29], off
	global_load_dword v148, v[30:31], off
	global_load_dword v149, v[32:33], off
	s_nop 0
	global_load_dword v150, v[34:35], off
	global_load_dword v151, v[36:37], off
	s_nop 0
	global_load_dword v152, v[20:21], off
	v_mov_b64_e32 v[162:163], v[2:3]
	v_lshl_add_u64 v[0:1], v[0:1], 0, s[34:35]
	v_lshl_add_u64 v[2:3], v[2:3], 0, s[6:7]
	v_cmp_lt_u64_e32 vcc, s[16:17], v[0:1]
	s_andn2_b64 exec, exec, vcc
	s_cbranch_execz .Lmod_e_done
	v_add_u32_e32 v4, 0xfffe5000, v0
	v_cmp_gt_u64_e32 vcc, s[12:13], v[0:1]
	s_mov_b64 s[0:1], 0x1afff
	v_cmp_lt_u64_e64 s[0:1], s[0:1], v[0:1]
	v_cndmask_b32_e32 v4, v4, v0, vcc
	v_mul_hi_u32 v29, v4, s2
	v_lshrrev_b32_e32 v29, 12, v29
	v_cndmask_b32_e64 v20, 0, 18, s[0:1]
	v_mul_u32_u24_e32 v30, 0x1800, v29
	v_mov_b32_e32 v21, v5
	v_cndmask_b32_e64 v19, 0, v6, s[0:1]
	v_cndmask_b32_e64 v22, 36, 54, s[0:1]
	v_cndmask_b32_e64 v23, v7, v8, s[0:1]
	v_cndmask_b32_e64 v24, v9, v10, s[0:1]
	v_cndmask_b32_e64 v25, v11, v12, s[0:1]
	v_cndmask_b32_e64 v26, v13, v14, s[0:1]
	v_cndmask_b32_e64 v27, v15, v16, s[0:1]
	v_cndmask_b32_e64 v28, v17, v18, s[0:1]
	v_add_u32_e32 v31, v20, v29
	v_sub_u32_e32 v20, v4, v30
	v_add_u32_e32 v32, v22, v29
	v_add_u32_e32 v33, v23, v29
	v_add_u32_e32 v34, v24, v29
	v_add_u32_e32 v35, v25, v29
	v_add_u32_e32 v36, v26, v29
	v_add_u32_e32 v37, v27, v29
	v_add_u32_e32 v38, v28, v29
	v_add_u32_e32 v4, v20, v19
	v_lshl_add_u64 v[20:21], v[20:21], 2, s[10:11]
	v_lshl_add_u64 v[22:23], v[4:5], 2, s[18:19]
	v_mad_u64_u32 v[24:25], s[0:1], v31, s3, v[20:21]
	v_mad_u64_u32 v[26:27], s[0:1], v32, s3, v[20:21]
	v_mad_u64_u32 v[28:29], s[0:1], v33, s3, v[20:21]
	v_mad_u64_u32 v[30:31], s[0:1], v34, s3, v[20:21]
	v_mad_u64_u32 v[32:33], s[0:1], v35, s3, v[20:21]
	v_mad_u64_u32 v[34:35], s[0:1], v36, s3, v[20:21]
	v_mad_u64_u32 v[36:37], s[0:1], v37, s3, v[20:21]
	v_mad_u64_u32 v[20:21], s[0:1], v38, s3, v[20:21]
	global_load_dword v153, v[22:23], off
	global_load_dword v154, v[24:25], off
	s_nop 0
	global_load_dword v155, v[26:27], off
	global_load_dword v156, v[28:29], off
	global_load_dword v157, v[30:31], off
	global_load_dword v158, v[32:33], off
	s_nop 0
	global_load_dword v159, v[34:35], off
	global_load_dword v160, v[36:37], off
	s_nop 0
	global_load_dword v161, v[20:21], off
	v_mov_b64_e32 v[164:165], v[2:3]

.LBB0_98:
	s_or_b64 exec, exec, s[12:13]
	s_cmp_eq_u32 s100, 1
	s_cbranch_scc0 .Lmod_l_done
	s_mov_b32 s100, 0
	s_waitcnt vmcnt(0)
	v_add_f32_e32 v144, v144, v145
	v_add_f32_e32 v144, v144, v146
	v_add_f32_e32 v144, v144, v147
	v_add_f32_e32 v144, v144, v148
	v_add_f32_e32 v144, v144, v149
	v_add_f32_e32 v144, v144, v150
	v_add_f32_e32 v144, v144, v151
	v_add_f32_e32 v144, v144, v152
	global_store_dword v[162:163], v144, off
	s_lshl_b32 s98, s96, 9
	v_add_u32_e32 v166, s98, v250
	v_cmp_gt_u32_e32 vcc, 0x16000, v166
	s_mov_b64 s[98:99], exec
	s_and_b64 exec, exec, vcc
	s_cbranch_execz .Lmod_l_skipb
	v_add_f32_e32 v153, v153, v154
	v_add_f32_e32 v153, v153, v155
	v_add_f32_e32 v153, v153, v156
	v_add_f32_e32 v153, v153, v157
	v_add_f32_e32 v153, v153, v158
	v_add_f32_e32 v153, v153, v159
	v_add_f32_e32 v153, v153, v160
	v_add_f32_e32 v153, v153, v161
	global_store_dword v[164:165], v153, off

.Lmod_l_done:
	s_min_i32 s14, s2, s24
	v_add_u32_e32 v78, s3, v82
	v_cmp_gt_i32_e32 vcc, s14, v78
	s_waitcnt lgkmcnt(0)
	s_barrier
	s_and_saveexec_b64 s[12:13], vcc
	s_cbranch_execz .LBB0_87
	v_and_b32_e32 v0, 64, v89
	v_add_u32_e32 v0, 64, v0
	v_xor_b32_e32 v1, 32, v89
	v_cmp_lt_i32_e32 vcc, v1, v0
	v_ashrrev_i32_e32 v79, 31, v78
	v_lshlrev_b64 v[80:81], 12, v[78:79]
	v_cndmask_b32_e32 v1, v89, v1, vcc
	v_lshlrev_b32_e32 v90, 2, v1
	v_xor_b32_e32 v1, 16, v89
	v_cmp_lt_i32_e32 vcc, v1, v0
	v_lshl_add_u64 v[80:81], v[68:69], 0, v[80:81]
	s_mov_b64 s[16:17], 0
	v_cndmask_b32_e32 v1, v89, v1, vcc
	v_lshlrev_b32_e32 v91, 2, v1
	v_xor_b32_e32 v1, 8, v89
	v_cmp_lt_i32_e32 vcc, v1, v0
	s_nop 1
	v_cndmask_b32_e32 v1, v89, v1, vcc
	v_lshlrev_b32_e32 v92, 2, v1
	v_xor_b32_e32 v1, 4, v89
	v_cmp_lt_i32_e32 vcc, v1, v0
	s_nop 1
	v_cndmask_b32_e32 v1, v89, v1, vcc
	v_lshlrev_b32_e32 v93, 2, v1
	v_xor_b32_e32 v1, 2, v89
	v_cmp_lt_i32_e32 vcc, v1, v0
	s_nop 1
	v_cndmask_b32_e32 v1, v89, v1, vcc
	v_lshlrev_b32_e32 v94, 2, v1
	v_xor_b32_e32 v1, 1, v89
	v_cmp_lt_i32_e32 vcc, v1, v0
	s_nop 1
	v_cndmask_b32_e32 v0, v89, v1, vcc
	v_lshlrev_b32_e32 v95, 2, v0
	ds_read_b128 v[0:3], v84
	ds_read_b128 v[4:7], v84 offset:1024
	ds_read_b128 v[8:11], v84 offset:8192
	ds_read_b128 v[12:15], v84 offset:9216
	ds_read_b128 v[16:19], v84 offset:2048
	ds_read_b128 v[20:23], v84 offset:3072
	ds_read_b128 v[24:27], v84 offset:10240
	ds_read_b128 v[28:31], v84 offset:11264
	ds_read_b128 v[32:35], v84 offset:4096
	ds_read_b128 v[36:39], v84 offset:5120
	ds_read_b128 v[40:43], v84 offset:12288
	ds_read_b128 v[44:47], v84 offset:13312
	ds_read_b128 v[48:51], v84 offset:6144
	ds_read_b128 v[52:55], v84 offset:7168
	ds_read_b128 v[56:59], v84 offset:14336
	ds_read_b128 v[60:63], v84 offset:15360
